# static s_setprio 1 for waves 0-3 (the other half) in the FoX-attention and dilated-attention phases
# baseline (speedup 1.0000x reference)
.LBB0_82:
	s_mov_b32 s1, 0x8000
	v_add_co_u32_e32 v2, vcc, s1, v0
	s_mov_b32 s1, 0xa000
	s_nop 0
	v_addc_co_u32_e32 v3, vcc, 0, v1, vcc
	v_add_co_u32_e32 v4, vcc, s1, v0
	s_mov_b32 s1, 0xc000
	s_nop 0
	v_addc_co_u32_e32 v5, vcc, 0, v1, vcc
	global_load_dwordx4 v[96:99], v[2:3], off
	global_load_dwordx4 v[102:105], v[4:5], off
	v_add_co_u32_e32 v2, vcc, s1, v0
	s_mov_b32 s1, 0xe000
	s_nop 0
	v_addc_co_u32_e32 v3, vcc, 0, v1, vcc
	v_add_co_u32_e32 v4, vcc, s1, v0
	s_mov_b32 s1, 0x10000
	s_nop 0
	v_addc_co_u32_e32 v5, vcc, 0, v1, vcc
	global_load_dwordx4 v[106:109], v[2:3], off
	global_load_dwordx4 v[110:113], v[4:5], off
	v_add_co_u32_e32 v2, vcc, s1, v0
	s_mov_b32 s1, 0x12000
	s_nop 0
	v_addc_co_u32_e32 v3, vcc, 0, v1, vcc
	v_add_co_u32_e32 v4, vcc, s1, v0
	s_mov_b32 s1, 0x14000
	s_nop 0
	v_addc_co_u32_e32 v5, vcc, 0, v1, vcc
	global_load_dwordx4 v[114:117], v[2:3], off
	global_load_dwordx4 v[118:121], v[4:5], off
	v_add_co_u32_e32 v2, vcc, s1, v0
	s_mov_b32 s1, 0x16000
	s_nop 0
	v_addc_co_u32_e32 v3, vcc, 0, v1, vcc
	v_add_co_u32_e32 v0, vcc, s1, v0
	s_mul_i32 s1, s21, 0xc0000
	s_nop 0
	v_addc_co_u32_e32 v1, vcc, 0, v1, vcc
	global_load_dwordx4 v[122:125], v[2:3], off
	global_load_dwordx4 v[126:129], v[0:1], off
	s_mul_hi_u32 s6, s20, 0xc0000
	s_add_i32 s6, s6, s1
	s_add_u32 s64, s44, 0x3b800000
	v_readlane_b32 s28, v242, 63
	s_addc_u32 s65, s45, 0
	s_lshl_b32 s7, s28, 7
	s_add_i32 s78, s7, 0
	s_lshl_b32 s7, s28, 12
	s_add_i32 s79, s7, 0
	s_mul_i32 s1, s20, 0xc0000
	s_lshl_b32 s69, s28, 5
	s_add_i32 s78, s78, 0x18400
	s_add_i32 s79, s79, 0x18800
	v_readlane_b32 s20, v242, 45
	v_readlane_b32 s21, v242, 46
	s_add_u32 s7, s12, s20
	s_addc_u32 s12, s13, s21
	v_readlane_b32 s13, v242, 47
	s_add_u32 s50, s7, s13
	s_addc_u32 s51, s12, 0
	s_add_u32 s42, s64, s1
	s_addc_u32 s43, s65, s6
	s_lshl_b32 s1, s28, 13
	s_cmp_lt_i32 s28, 4
	s_cselect_b64 s[12:13], -1, 0
	s_cmp_lt_i32 s28, 3
	s_cselect_b64 s[20:21], -1, 0
	s_cmp_lt_i32 s28, 2
	s_cselect_b64 s[22:23], -1, 0
	s_cmp_lt_i32 s28, 1
	s_cselect_b64 s[24:25], -1, 0
	s_cmp_lt_i32 s28, 0
	s_cselect_b64 s[40:41], -1, 0
	s_add_i32 s80, s1, 0
	v_readlane_b32 s1, v242, 21
	s_mov_b32 s66, s1
	v_readlane_b32 s81, v242, 37
	v_readlane_b32 s67, v242, 34
	v_readlane_b32 s84, v242, 20
	v_readlane_b32 s89, v243, 63
	s_waitcnt lgkmcnt(0)
	v_lshlrev_b32_e32 v244, 2, v225
	global_load_dword v245, v244, s[2:3]
	v_and_b32_e32 v246, 0xff, v225
	v_lshlrev_b32_e32 v246, 2, v246
	global_load_dword v247, v246, s[2:3] offset:2048
	s_waitcnt vmcnt(0)
	v_add_u32_e32 v244, 0x21000, v244
	ds_write_b32 v244, v245
	v_add_u32_e32 v246, 0x21800, v246
	ds_write_b32 v246, v247
	s_waitcnt lgkmcnt(0)
	s_barrier
	s_mov_b32 s100, 0
	v_readfirstlane_b32 s101, v225
	s_lshr_b32 s101, s101, 6
	s_cmp_lt_u32 s101, 4
	s_cbranch_scc0 .Lmy_prio_b
	s_setprio 1

.LBB0_222:
	s_and_b64 vcc, exec, s[42:43]
	s_cbranch_vccz .LBB0_368
	s_getreg_b32 s1, hwreg(HW_REG_XCC_ID, 0, 4)
	v_cmp_eq_u32_e32 vcc, 0, v225
	s_waitcnt lgkmcnt(0)
	s_and_saveexec_b64 s[2:3], vcc
	v_mov_b32_e32 v0, s46
	ds_write_b32 v0, v215
	s_or_b64 exec, exec, s[2:3]
	s_add_u32 s65, s44, 0xb800000
	s_addc_u32 s70, s45, 0
	s_add_u32 s14, s44, 0x13800000
	s_addc_u32 s15, s45, 0
	s_add_u32 s71, s44, 0x1b800000
	s_addc_u32 s72, s45, 0
	s_add_u32 s73, s44, 0x2c000000
	s_addc_u32 s64, s45, 0
	s_add_u32 s12, s44, 0x23800000
	s_addc_u32 s13, s45, 0
	s_add_u32 s4, s44, 0x2b800000
	s_addc_u32 s5, s45, 0
	s_add_u32 s26, s44, 0x2bc00000
	v_readlane_b32 s2, v242, 2
	s_addc_u32 s27, s45, 0
	v_readlane_b32 s3, v242, 3
	s_mov_b32 s6, s2
	s_ashr_i32 s7, s2, 31
	s_lshl_b64 s[2:3], s[6:7], 17
	s_add_u32 s2, s44, s2
	s_addc_u32 s3, s45, s3
	s_add_u32 s35, s2, 0xc0000
	s_mov_b32 s2, s6
	s_addc_u32 s80, s3, 0
	v_writelane_b32 v242, s2, 2
	s_waitcnt vmcnt(0) lgkmcnt(0)
	s_barrier
	v_writelane_b32 v242, s3, 3
	s_lshl_b32 s2, s6, 9
	s_ashr_i32 s3, s2, 31
	s_lshl_b64 s[2:3], s[2:3], 2
	s_add_u32 s2, s44, s2
	s_addc_u32 s3, s45, s3
	s_add_u32 s6, s2, 0x100000
	s_addc_u32 s7, s3, 0
	s_and_b32 s81, s1, 7
	s_lshl_b32 s2, s81, 8
	s_add_u32 s58, s6, s2
	s_addc_u32 s59, s7, 0
	s_add_i32 s2, s1, 1
	s_and_b32 s2, s2, 7
	s_lshl_b32 s3, s2, 8
	s_add_u32 s74, s6, s3
	s_addc_u32 s75, s7, 0
	s_add_i32 s3, s1, 2
	s_and_b32 s3, s3, 7
	s_lshl_b32 s8, s3, 8
	s_add_u32 s76, s6, s8
	s_addc_u32 s77, s7, 0
	s_add_i32 s8, s1, 3
	s_and_b32 s8, s8, 7
	v_writelane_b32 v241, s8, 10
	s_lshl_b32 s8, s8, 8
	s_add_u32 s8, s6, s8
	s_addc_u32 s9, s7, 0
	v_writelane_b32 v241, s8, 12
	s_nop 1
	v_writelane_b32 v241, s9, 13
	s_xor_b32 s8, s81, 4
	v_writelane_b32 v241, s8, 14
	s_lshl_b32 s8, s8, 8
	s_add_u32 s8, s6, s8
	s_addc_u32 s9, s7, 0
	v_writelane_b32 v241, s8, 15
	s_nop 1
	v_writelane_b32 v241, s9, 16
	s_add_i32 s8, s1, 5
	s_and_b32 s8, s8, 7
	v_writelane_b32 v241, s8, 17
	s_lshl_b32 s8, s8, 8
	s_add_u32 s8, s6, s8
	s_addc_u32 s9, s7, 0
	v_writelane_b32 v241, s8, 18
	s_nop 1
	v_writelane_b32 v241, s9, 19
	s_add_i32 s8, s1, 6
	s_and_b32 s8, s8, 7
	v_writelane_b32 v241, s8, 20
	s_lshl_b32 s8, s8, 8
	s_add_u32 s8, s6, s8
	s_addc_u32 s9, s7, 0
	v_writelane_b32 v241, s8, 21
	s_add_i32 s1, s1, -1
	s_and_b32 s1, s1, 7
	v_writelane_b32 v241, s9, 22
	v_writelane_b32 v241, s1, 23
	s_lshl_b32 s1, s1, 8
	s_add_u32 s6, s6, s1
	s_addc_u32 s7, s7, 0
	v_writelane_b32 v241, s6, 24
	s_lshl_b32 s98, s81, 9
	s_nop 0
	v_writelane_b32 v241, s7, 25
	v_readfirstlane_b32 s100, v225
	s_lshr_b32 s100, s100, 6
	s_cmp_lt_u32 s100, 4
	s_cbranch_scc0 .Lmy_prio_f
	s_setprio 1
